# sample S5 item: four tokens' u rows loaded with the item tables, token loop unrolled (no per-token load wait); on top of v51
# speedup vs baseline: 1.0376x; 1.0041x over previous
.LBB0_1076:
	s_or_b64 exec, exec, s[4:5]
	s_lshl_b32 s4, s52, 3
	s_add_i32 s4, s4, s67
	s_and_b32 s5, s4, 31
	s_lshl_b32 s44, s5, 6
	v_add_u32_e32 v22, s44, v18
	s_lshr_b32 s52, s4, 5
	v_ashrrev_i32_e32 v23, 31, v22
	s_mul_i32 s4, s5, 0x3c0
	v_lshlrev_b64 v[2:3], 5, v[22:23]
	v_lshlrev_b64 v[4:5], 7, v[22:23]
	v_add_u32_e32 v22, s4, v22
	v_readlane_b32 s68, v252, 24
	v_ashrrev_i32_e32 v23, 31, v22
	v_readlane_b32 s69, v252, 25
	v_readlane_b32 s70, v252, 26
	v_readlane_b32 s71, v252, 27
	v_readlane_b32 s80, v252, 36
	v_readlane_b32 s81, v252, 37
	v_lshlrev_b64 v[22:23], 2, v[22:23]
	v_readlane_b32 s82, v252, 38
	v_readlane_b32 s83, v252, 39
	s_mov_b64 s[68:69], s[80:81]
	v_lshl_add_u64 v[2:3], s[54:55], 0, v[2:3]
	v_lshl_add_u64 v[14:15], s[56:57], 0, v[4:5]
	s_mov_b64 s[70:71], s[82:83]
	v_lshl_add_u64 v[24:25], s[68:69], 0, v[22:23]
	global_load_dwordx2 v[44:45], v[2:3], off
	global_load_dwordx4 v[98:101], v[14:15], off
	global_load_dwordx4 v[40:43], v[14:15], off offset:16
	global_load_dwordx4 v[36:39], v[14:15], off offset:32
	global_load_dwordx4 v[32:35], v[14:15], off offset:48
	s_nop 0
	global_load_dwordx4 v[2:5], v[14:15], off offset:64
	global_load_dwordx4 v[6:9], v[14:15], off offset:80
	global_load_dwordx4 v[10:13], v[14:15], off offset:96
	s_nop 0
	global_load_dwordx4 v[14:17], v[14:15], off offset:112
	v_lshl_add_u64 v[22:23], s[70:71], 0, v[22:23]
	global_load_dword v51, v[24:25], off
	global_load_dword v53, v[24:25], off offset:256
	global_load_dword v55, v[24:25], off offset:512
	global_load_dword v57, v[24:25], off offset:768
	global_load_dword v59, v[24:25], off offset:1024
	global_load_dword v61, v[24:25], off offset:1280
	global_load_dword v63, v[24:25], off offset:1536
	global_load_dword v65, v[24:25], off offset:1792
	global_load_dword v67, v[22:23], off
	global_load_dword v69, v[22:23], off offset:256
	global_load_dword v71, v[22:23], off offset:512
	global_load_dword v73, v[22:23], off offset:768
	global_load_dword v75, v[22:23], off offset:1024
	global_load_dword v77, v[22:23], off offset:1280
	global_load_dword v78, v[22:23], off offset:1536
	global_load_dword v79, v[22:23], off offset:1792
	global_load_dword v80, v[24:25], off offset:2048
	global_load_dword v81, v[24:25], off offset:2304
	global_load_dword v82, v[24:25], off offset:2560
	global_load_dword v83, v[24:25], off offset:2816
	global_load_dword v84, v[24:25], off offset:3072
	global_load_dword v85, v[24:25], off offset:3328
	global_load_dword v86, v[24:25], off offset:3584
	global_load_dword v87, v[24:25], off offset:3840
	global_load_dword v88, v[22:23], off offset:2048
	global_load_dword v89, v[22:23], off offset:2304
	global_load_dword v90, v[22:23], off offset:2560
	global_load_dword v91, v[22:23], off offset:2816
	global_load_dword v92, v[22:23], off offset:3072
	global_load_dword v93, v[22:23], off offset:3328
	global_load_dword v94, v[22:23], off offset:3584
	global_load_dword v95, v[22:23], off offset:3840
	s_lshl_b32 s4, s52, 11
	s_or_b32 s4, s44, s4
	v_add_u32_e32 v22, s4, v18
	v_ashrrev_i32_e32 v23, 31, v22
	v_readlane_b32 s76, v252, 32
	v_readlane_b32 s77, v252, 33
	v_readlane_b32 s78, v252, 34
	v_readlane_b32 s79, v252, 35
	v_lshlrev_b64 v[24:25], 2, v[22:23]
	v_lshl_add_u64 v[22:23], s[48:49], 0, v[24:25]
	v_readlane_b32 s76, v252, 48
	global_load_dword v23, v[22:23], off
	v_lshl_or_b32 v22, v1, 2, s44
	v_readlane_b32 s77, v252, 49
	v_lshl_add_u64 v[24:25], s[50:51], 0, v[24:25]
	s_nop 3
	global_load_dword v96, v22, s[76:77]
	s_nop 0
	global_load_dword v22, v[24:25], off
	s_lshl_b64 s[44:45], s[52:53], 12
	s_lshl_b32 s5, s5, 5
	s_or_b32 s44, s44, s5
	s_add_u32 s5, s3, s44
	s_addc_u32 s52, s33, s45
	s_mov_b32 s60, s5
	s_mov_b32 s61, s52
	global_load_dwordx4 v[162:165], v47, s[60:61] offset:-16
	global_load_dwordx4 v[166:169], v47, s[60:61] offset:0
	global_load_ushort v170, v106, s[60:61] offset:-16
	global_load_dwordx4 v[130:133], v47, s[60:61] offset:1008
	global_load_dwordx4 v[134:137], v47, s[60:61] offset:1024
	global_load_ushort v171, v106, s[60:61] offset:1008
	global_load_dwordx4 v[138:141], v47, s[60:61] offset:2032
	global_load_dwordx4 v[142:145], v47, s[60:61] offset:2048
	global_load_ushort v172, v106, s[60:61] offset:2032
	global_load_dwordx4 v[150:153], v47, s[60:61] offset:3056
	global_load_dwordx4 v[154:157], v47, s[60:61] offset:3072
	global_load_ushort v173, v106, s[60:61] offset:3056
	v_readlane_b32 s72, v252, 28
	v_readlane_b32 s73, v252, 29
	v_readlane_b32 s74, v252, 30
	v_readlane_b32 s75, v252, 31
	v_readlane_b32 s78, v252, 50
	v_readlane_b32 s79, v252, 51
	v_readlane_b32 s80, v252, 52
	v_readlane_b32 s81, v252, 53
	v_readlane_b32 s82, v252, 54
	v_readlane_b32 s83, v252, 55
	s_waitcnt vmcnt(55)
	v_pk_add_f32 v[26:27], v[44:45], 0 neg_lo:[1,1] neg_hi:[1,1]
	v_mov_b32_e32 v24, v44
	v_mov_b32_e32 v25, v44
	v_mov_b32_e32 v26, v45
	s_waitcnt vmcnt(51)
	v_mov_b32_e32 v29, v35
	v_mov_b32_e32 v31, v33
	v_mov_b32_e32 v33, v39
	v_mov_b32_e32 v35, v37
	s_waitcnt vmcnt(47)
	v_mov_b32_e32 v28, v17
	v_mov_b32_e32 v17, v34
	v_mov_b32_e32 v30, v15
	v_mov_b32_e32 v15, v32
	v_mov_b32_e32 v32, v13
	v_mov_b32_e32 v13, v38
	v_mov_b32_e32 v34, v11
	v_mov_b32_e32 v11, v36
	v_mov_b32_e32 v36, v9
	v_mov_b32_e32 v37, v43
	v_mov_b32_e32 v9, v42
	v_mov_b32_e32 v38, v7
	v_mov_b32_e32 v39, v41
	v_mov_b32_e32 v7, v40
	v_mov_b32_e32 v40, v5
	v_mov_b32_e32 v41, v101
	v_mov_b32_e32 v5, v100
	v_mov_b32_e32 v42, v3
	v_mov_b32_e32 v43, v99
	v_mov_b32_e32 v3, v98
	v_lshl_add_u64 v[44:45], v[20:21], 0, s[44:45]
	s_mov_b64 s[44:45], 0
	s_waitcnt vmcnt(0)
	v_lshlrev_b32_e32 v46, 16, v162
	v_and_b32_e32 v48, 0xffff0000, v162
	v_lshlrev_b32_e32 v50, 16, v163
	v_and_b32_e32 v52, 0xffff0000, v163
	v_pk_fma_f32 v[98:99], v[2:3], v[46:47], 0 op_sel_hi:[1,0,0]
	v_lshlrev_b32_e32 v54, 16, v164
	v_pk_fma_f32 v[98:99], v[42:43], v[48:49], v[98:99] op_sel_hi:[1,0,1]
	v_and_b32_e32 v56, 0xffff0000, v164
	v_pk_fma_f32 v[98:99], v[4:5], v[50:51], v[98:99] op_sel_hi:[1,0,1]
	v_lshlrev_b32_e32 v58, 16, v165
	v_pk_fma_f32 v[98:99], v[40:41], v[52:53], v[98:99] op_sel_hi:[1,0,1]
	v_and_b32_e32 v60, 0xffff0000, v165
	v_pk_fma_f32 v[98:99], v[6:7], v[54:55], v[98:99] op_sel_hi:[1,0,1]
	v_lshlrev_b32_e32 v62, 16, v166
	v_pk_fma_f32 v[98:99], v[38:39], v[56:57], v[98:99] op_sel_hi:[1,0,1]
	v_and_b32_e32 v64, 0xffff0000, v166
	v_pk_fma_f32 v[98:99], v[8:9], v[58:59], v[98:99] op_sel_hi:[1,0,1]
	v_lshlrev_b32_e32 v66, 16, v167
	v_pk_fma_f32 v[98:99], v[36:37], v[60:61], v[98:99] op_sel_hi:[1,0,1]
	v_and_b32_e32 v68, 0xffff0000, v167
	v_pk_fma_f32 v[98:99], v[10:11], v[62:63], v[98:99] op_sel_hi:[1,0,1]
	v_lshlrev_b32_e32 v70, 16, v168
	v_pk_fma_f32 v[98:99], v[34:35], v[64:65], v[98:99] op_sel_hi:[1,0,1]
	v_and_b32_e32 v72, 0xffff0000, v168
	v_pk_fma_f32 v[98:99], v[12:13], v[66:67], v[98:99] op_sel_hi:[1,0,1]
	v_lshlrev_b32_e32 v74, 16, v169
	v_pk_fma_f32 v[98:99], v[32:33], v[68:69], v[98:99] op_sel_hi:[1,0,1]
	v_and_b32_e32 v76, 0xffff0000, v169
	v_pk_fma_f32 v[98:99], v[14:15], v[70:71], v[98:99] op_sel_hi:[1,0,1]
	s_nop 0
	v_pk_fma_f32 v[98:99], v[30:31], v[72:73], v[98:99] op_sel_hi:[1,0,1]
	s_nop 0
	v_pk_fma_f32 v[98:99], v[16:17], v[74:75], v[98:99] op_sel_hi:[1,0,1]
	s_nop 0
	v_pk_fma_f32 v[98:99], v[28:29], v[76:77], v[98:99] op_sel_hi:[1,0,1]
	s_nop 0
	v_pk_fma_f32 v[98:99], v[26:27], v[22:23], v[98:99] op_sel:[0,1,0] op_sel_hi:[1,0,1]
	s_nop 0
	v_pk_fma_f32 v[22:23], v[24:25], v[22:23], v[98:99]
	s_nop 0
	v_mul_f32_e32 v97, v67, v22
	v_mul_f32_e32 v98, v69, v22
	v_mul_f32_e32 v99, v71, v22
	v_mul_f32_e32 v100, v73, v22
	v_mul_f32_e32 v101, v75, v22
	v_mul_f32_e32 v102, v77, v22
	v_mul_f32_e32 v109, v78, v22
	v_mul_f32_e32 v111, v79, v22
	v_mul_f32_e32 v113, v88, v22
	v_mul_f32_e32 v115, v89, v22
	v_mul_f32_e32 v117, v90, v22
	v_mul_f32_e32 v119, v91, v22
	v_mul_f32_e32 v121, v92, v22
	v_mul_f32_e32 v123, v93, v22
	v_mul_f32_e32 v125, v94, v22
	v_mul_f32_e32 v127, v95, v22
	v_fma_f32 v97, v51, v23, -v97
	v_fma_f32 v98, v53, v23, -v98
	v_fma_f32 v99, v55, v23, -v99
	v_fma_f32 v100, v57, v23, -v100
	v_fma_f32 v101, v59, v23, -v101
	v_fma_f32 v102, v61, v23, -v102
	v_fma_f32 v109, v63, v23, -v109
	v_fma_f32 v111, v65, v23, -v111
	v_fma_f32 v113, v80, v23, -v113
	v_fma_f32 v115, v81, v23, -v115
	v_fma_f32 v117, v82, v23, -v117
	v_fma_f32 v119, v83, v23, -v119
	v_fma_f32 v121, v84, v23, -v121
	v_fma_f32 v123, v85, v23, -v123
	v_fma_f32 v125, v86, v23, -v125
	v_fma_f32 v127, v87, v23, -v127
	v_add_f32_dpp v97, v97, v97 row_ror:8 row_mask:0xf bank_mask:0xf bound_ctrl:1
	v_add_f32_dpp v98, v98, v98 row_ror:8 row_mask:0xf bank_mask:0xf bound_ctrl:1
	v_add_f32_dpp v99, v99, v99 row_ror:8 row_mask:0xf bank_mask:0xf bound_ctrl:1
	v_add_f32_dpp v100, v100, v100 row_ror:8 row_mask:0xf bank_mask:0xf bound_ctrl:1
	v_add_f32_dpp v101, v101, v101 row_ror:8 row_mask:0xf bank_mask:0xf bound_ctrl:1
	v_add_f32_dpp v102, v102, v102 row_ror:8 row_mask:0xf bank_mask:0xf bound_ctrl:1
	v_add_f32_dpp v109, v109, v109 row_ror:8 row_mask:0xf bank_mask:0xf bound_ctrl:1
	v_add_f32_dpp v111, v111, v111 row_ror:8 row_mask:0xf bank_mask:0xf bound_ctrl:1
	v_add_f32_dpp v113, v113, v113 row_ror:8 row_mask:0xf bank_mask:0xf bound_ctrl:1
	v_add_f32_dpp v115, v115, v115 row_ror:8 row_mask:0xf bank_mask:0xf bound_ctrl:1
	v_add_f32_dpp v117, v117, v117 row_ror:8 row_mask:0xf bank_mask:0xf bound_ctrl:1
	v_add_f32_dpp v119, v119, v119 row_ror:8 row_mask:0xf bank_mask:0xf bound_ctrl:1
	v_add_f32_dpp v121, v121, v121 row_ror:8 row_mask:0xf bank_mask:0xf bound_ctrl:1
	v_add_f32_dpp v123, v123, v123 row_ror:8 row_mask:0xf bank_mask:0xf bound_ctrl:1
	v_add_f32_dpp v125, v125, v125 row_ror:8 row_mask:0xf bank_mask:0xf bound_ctrl:1
	v_add_f32_dpp v127, v127, v127 row_ror:8 row_mask:0xf bank_mask:0xf bound_ctrl:1
	v_cndmask_b32_e64 v97, v97, v113, s[6:7]
	v_cndmask_b32_e64 v98, v98, v115, s[6:7]
	v_cndmask_b32_e64 v99, v99, v117, s[6:7]
	v_cndmask_b32_e64 v100, v100, v119, s[6:7]
	v_cndmask_b32_e64 v101, v101, v121, s[6:7]
	v_cndmask_b32_e64 v102, v102, v123, s[6:7]
	v_cndmask_b32_e64 v109, v109, v125, s[6:7]
	v_cndmask_b32_e64 v111, v111, v127, s[6:7]
	v_add_f32_dpp v97, v97, v97 row_half_mirror row_mask:0xf bank_mask:0xf bound_ctrl:1
	v_add_f32_dpp v98, v98, v98 row_half_mirror row_mask:0xf bank_mask:0xf bound_ctrl:1
	v_add_f32_dpp v99, v99, v99 row_half_mirror row_mask:0xf bank_mask:0xf bound_ctrl:1
	v_add_f32_dpp v100, v100, v100 row_half_mirror row_mask:0xf bank_mask:0xf bound_ctrl:1
	v_add_f32_dpp v101, v101, v101 row_half_mirror row_mask:0xf bank_mask:0xf bound_ctrl:1
	v_add_f32_dpp v102, v102, v102 row_half_mirror row_mask:0xf bank_mask:0xf bound_ctrl:1
	v_add_f32_dpp v109, v109, v109 row_half_mirror row_mask:0xf bank_mask:0xf bound_ctrl:1
	v_add_f32_dpp v111, v111, v111 row_half_mirror row_mask:0xf bank_mask:0xf bound_ctrl:1
	v_cndmask_b32_e64 v97, v97, v101, s[8:9]
	v_cndmask_b32_e64 v98, v98, v102, s[8:9]
	v_cndmask_b32_e64 v99, v99, v109, s[8:9]
	v_cndmask_b32_e64 v100, v100, v111, s[8:9]
	v_add_f32_dpp v97, v97, v97 quad_perm:[3,2,1,0] row_mask:0xf bank_mask:0xf bound_ctrl:1
	v_add_f32_dpp v98, v98, v98 quad_perm:[3,2,1,0] row_mask:0xf bank_mask:0xf bound_ctrl:1
	v_add_f32_dpp v99, v99, v99 quad_perm:[3,2,1,0] row_mask:0xf bank_mask:0xf bound_ctrl:1
	v_add_f32_dpp v100, v100, v100 quad_perm:[3,2,1,0] row_mask:0xf bank_mask:0xf bound_ctrl:1
	v_cndmask_b32_e64 v97, v97, v99, s[10:11]
	v_cndmask_b32_e64 v98, v98, v100, s[10:11]
	s_nop 1
	v_add_f32_dpp v97, v97, v97 quad_perm:[1,0,3,2] row_mask:0xf bank_mask:0xf bound_ctrl:1
	v_add_f32_dpp v98, v98, v98 quad_perm:[1,0,3,2] row_mask:0xf bank_mask:0xf bound_ctrl:1
	v_cndmask_b32_e64 v97, v97, v98, s[12:13]
	v_mov_b32_e32 v110, v97
	s_nop 1
	v_permlane16_swap_b32_e32 v97, v110
	v_add_f32_e32 v97, v97, v110
	v_mov_b32_e32 v110, v97
	s_nop 1
	v_permlane32_swap_b32_e32 v97, v110
	s_and_saveexec_b64 s[60:61], s[0:1]
	s_cbranch_execz .Lsmp_skip_0
	v_add_f32_e32 v97, v97, v110
	v_lshlrev_b32_e32 v46, 16, v170
	v_fma_f32 v48, v96, v46, v97
	v_mul_f32_e32 v46, 0x3d372713, v48
	v_mul_f32_e32 v46, v48, v46
	v_fma_f32 v46, v48, v46, v48
	v_mul_f32_e32 v46, 0xbfcc422a, v46
	v_mul_f32_e32 v46, 0x3fb8aa3b, v46
	v_exp_f32_e32 v46, v46
	v_lshl_add_u64 v[98:99], v[44:45], 0, s[44:45]
	v_add_f32_e32 v46, 1.0, v46
	v_rcp_f32_e32 v46, v46
	s_nop 0
	v_mul_f32_e32 v46, v48, v46
	v_cvt_pk_bf16_f32 v46, v46, v46
	global_store_short v[98:99], v46, off
.Lsmp_skip_0:
	s_or_b64 exec, exec, s[60:61]
	s_add_u32 s44, s44, 0x400
	s_addc_u32 s45, s45, 0
	v_lshlrev_b32_e32 v46, 16, v130
	v_and_b32_e32 v48, 0xffff0000, v130
	v_lshlrev_b32_e32 v50, 16, v131
	v_and_b32_e32 v52, 0xffff0000, v131
	v_pk_fma_f32 v[98:99], v[2:3], v[46:47], 0 op_sel_hi:[1,0,0]
	v_lshlrev_b32_e32 v54, 16, v132
	v_pk_fma_f32 v[98:99], v[42:43], v[48:49], v[98:99] op_sel_hi:[1,0,1]
	v_and_b32_e32 v56, 0xffff0000, v132
	v_pk_fma_f32 v[98:99], v[4:5], v[50:51], v[98:99] op_sel_hi:[1,0,1]
	v_lshlrev_b32_e32 v58, 16, v133
	v_pk_fma_f32 v[98:99], v[40:41], v[52:53], v[98:99] op_sel_hi:[1,0,1]
	v_and_b32_e32 v60, 0xffff0000, v133
	v_pk_fma_f32 v[98:99], v[6:7], v[54:55], v[98:99] op_sel_hi:[1,0,1]
	v_lshlrev_b32_e32 v62, 16, v134
	v_pk_fma_f32 v[98:99], v[38:39], v[56:57], v[98:99] op_sel_hi:[1,0,1]
	v_and_b32_e32 v64, 0xffff0000, v134
	v_pk_fma_f32 v[98:99], v[8:9], v[58:59], v[98:99] op_sel_hi:[1,0,1]
	v_lshlrev_b32_e32 v66, 16, v135
	v_pk_fma_f32 v[98:99], v[36:37], v[60:61], v[98:99] op_sel_hi:[1,0,1]
	v_and_b32_e32 v68, 0xffff0000, v135
	v_pk_fma_f32 v[98:99], v[10:11], v[62:63], v[98:99] op_sel_hi:[1,0,1]
	v_lshlrev_b32_e32 v70, 16, v136
	v_pk_fma_f32 v[98:99], v[34:35], v[64:65], v[98:99] op_sel_hi:[1,0,1]
	v_and_b32_e32 v72, 0xffff0000, v136
	v_pk_fma_f32 v[98:99], v[12:13], v[66:67], v[98:99] op_sel_hi:[1,0,1]
	v_lshlrev_b32_e32 v74, 16, v137
	v_pk_fma_f32 v[98:99], v[32:33], v[68:69], v[98:99] op_sel_hi:[1,0,1]
	v_and_b32_e32 v76, 0xffff0000, v137
	v_pk_fma_f32 v[98:99], v[14:15], v[70:71], v[98:99] op_sel_hi:[1,0,1]
	s_nop 0
	v_pk_fma_f32 v[98:99], v[30:31], v[72:73], v[98:99] op_sel_hi:[1,0,1]
	s_nop 0
	v_pk_fma_f32 v[98:99], v[16:17], v[74:75], v[98:99] op_sel_hi:[1,0,1]
	s_nop 0
	v_pk_fma_f32 v[98:99], v[28:29], v[76:77], v[98:99] op_sel_hi:[1,0,1]
	s_nop 0
	v_pk_fma_f32 v[98:99], v[26:27], v[22:23], v[98:99] op_sel:[0,1,0] op_sel_hi:[1,0,1]
	s_nop 0
	v_pk_fma_f32 v[22:23], v[24:25], v[22:23], v[98:99]
	s_nop 0
	v_mul_f32_e32 v97, v67, v22
	v_mul_f32_e32 v98, v69, v22
	v_mul_f32_e32 v99, v71, v22
	v_mul_f32_e32 v100, v73, v22
	v_mul_f32_e32 v101, v75, v22
	v_mul_f32_e32 v102, v77, v22
	v_mul_f32_e32 v109, v78, v22
	v_mul_f32_e32 v111, v79, v22
	v_mul_f32_e32 v113, v88, v22
	v_mul_f32_e32 v115, v89, v22
	v_mul_f32_e32 v117, v90, v22
	v_mul_f32_e32 v119, v91, v22
	v_mul_f32_e32 v121, v92, v22
	v_mul_f32_e32 v123, v93, v22
	v_mul_f32_e32 v125, v94, v22
	v_mul_f32_e32 v127, v95, v22
	v_fma_f32 v97, v51, v23, -v97
	v_fma_f32 v98, v53, v23, -v98
	v_fma_f32 v99, v55, v23, -v99
	v_fma_f32 v100, v57, v23, -v100
	v_fma_f32 v101, v59, v23, -v101
	v_fma_f32 v102, v61, v23, -v102
	v_fma_f32 v109, v63, v23, -v109
	v_fma_f32 v111, v65, v23, -v111
	v_fma_f32 v113, v80, v23, -v113
	v_fma_f32 v115, v81, v23, -v115
	v_fma_f32 v117, v82, v23, -v117
	v_fma_f32 v119, v83, v23, -v119
	v_fma_f32 v121, v84, v23, -v121
	v_fma_f32 v123, v85, v23, -v123
	v_fma_f32 v125, v86, v23, -v125
	v_fma_f32 v127, v87, v23, -v127
	v_add_f32_dpp v97, v97, v97 row_ror:8 row_mask:0xf bank_mask:0xf bound_ctrl:1
	v_add_f32_dpp v98, v98, v98 row_ror:8 row_mask:0xf bank_mask:0xf bound_ctrl:1
	v_add_f32_dpp v99, v99, v99 row_ror:8 row_mask:0xf bank_mask:0xf bound_ctrl:1
	v_add_f32_dpp v100, v100, v100 row_ror:8 row_mask:0xf bank_mask:0xf bound_ctrl:1
	v_add_f32_dpp v101, v101, v101 row_ror:8 row_mask:0xf bank_mask:0xf bound_ctrl:1
	v_add_f32_dpp v102, v102, v102 row_ror:8 row_mask:0xf bank_mask:0xf bound_ctrl:1
	v_add_f32_dpp v109, v109, v109 row_ror:8 row_mask:0xf bank_mask:0xf bound_ctrl:1
	v_add_f32_dpp v111, v111, v111 row_ror:8 row_mask:0xf bank_mask:0xf bound_ctrl:1
	v_add_f32_dpp v113, v113, v113 row_ror:8 row_mask:0xf bank_mask:0xf bound_ctrl:1
	v_add_f32_dpp v115, v115, v115 row_ror:8 row_mask:0xf bank_mask:0xf bound_ctrl:1
	v_add_f32_dpp v117, v117, v117 row_ror:8 row_mask:0xf bank_mask:0xf bound_ctrl:1
	v_add_f32_dpp v119, v119, v119 row_ror:8 row_mask:0xf bank_mask:0xf bound_ctrl:1
	v_add_f32_dpp v121, v121, v121 row_ror:8 row_mask:0xf bank_mask:0xf bound_ctrl:1
	v_add_f32_dpp v123, v123, v123 row_ror:8 row_mask:0xf bank_mask:0xf bound_ctrl:1
	v_add_f32_dpp v125, v125, v125 row_ror:8 row_mask:0xf bank_mask:0xf bound_ctrl:1
	v_add_f32_dpp v127, v127, v127 row_ror:8 row_mask:0xf bank_mask:0xf bound_ctrl:1
	v_cndmask_b32_e64 v97, v97, v113, s[6:7]
	v_cndmask_b32_e64 v98, v98, v115, s[6:7]
	v_cndmask_b32_e64 v99, v99, v117, s[6:7]
	v_cndmask_b32_e64 v100, v100, v119, s[6:7]
	v_cndmask_b32_e64 v101, v101, v121, s[6:7]
	v_cndmask_b32_e64 v102, v102, v123, s[6:7]
	v_cndmask_b32_e64 v109, v109, v125, s[6:7]
	v_cndmask_b32_e64 v111, v111, v127, s[6:7]
	v_add_f32_dpp v97, v97, v97 row_half_mirror row_mask:0xf bank_mask:0xf bound_ctrl:1
	v_add_f32_dpp v98, v98, v98 row_half_mirror row_mask:0xf bank_mask:0xf bound_ctrl:1
	v_add_f32_dpp v99, v99, v99 row_half_mirror row_mask:0xf bank_mask:0xf bound_ctrl:1
	v_add_f32_dpp v100, v100, v100 row_half_mirror row_mask:0xf bank_mask:0xf bound_ctrl:1
	v_add_f32_dpp v101, v101, v101 row_half_mirror row_mask:0xf bank_mask:0xf bound_ctrl:1
	v_add_f32_dpp v102, v102, v102 row_half_mirror row_mask:0xf bank_mask:0xf bound_ctrl:1
	v_add_f32_dpp v109, v109, v109 row_half_mirror row_mask:0xf bank_mask:0xf bound_ctrl:1
	v_add_f32_dpp v111, v111, v111 row_half_mirror row_mask:0xf bank_mask:0xf bound_ctrl:1
	v_cndmask_b32_e64 v97, v97, v101, s[8:9]
	v_cndmask_b32_e64 v98, v98, v102, s[8:9]
	v_cndmask_b32_e64 v99, v99, v109, s[8:9]
	v_cndmask_b32_e64 v100, v100, v111, s[8:9]
	v_add_f32_dpp v97, v97, v97 quad_perm:[3,2,1,0] row_mask:0xf bank_mask:0xf bound_ctrl:1
	v_add_f32_dpp v98, v98, v98 quad_perm:[3,2,1,0] row_mask:0xf bank_mask:0xf bound_ctrl:1
	v_add_f32_dpp v99, v99, v99 quad_perm:[3,2,1,0] row_mask:0xf bank_mask:0xf bound_ctrl:1
	v_add_f32_dpp v100, v100, v100 quad_perm:[3,2,1,0] row_mask:0xf bank_mask:0xf bound_ctrl:1
	v_cndmask_b32_e64 v97, v97, v99, s[10:11]
	v_cndmask_b32_e64 v98, v98, v100, s[10:11]
	s_nop 1
	v_add_f32_dpp v97, v97, v97 quad_perm:[1,0,3,2] row_mask:0xf bank_mask:0xf bound_ctrl:1
	v_add_f32_dpp v98, v98, v98 quad_perm:[1,0,3,2] row_mask:0xf bank_mask:0xf bound_ctrl:1
	v_cndmask_b32_e64 v97, v97, v98, s[12:13]
	v_mov_b32_e32 v110, v97
	s_nop 1
	v_permlane16_swap_b32_e32 v97, v110
	v_add_f32_e32 v97, v97, v110
	v_mov_b32_e32 v110, v97
	s_nop 1
	v_permlane32_swap_b32_e32 v97, v110
	s_and_saveexec_b64 s[60:61], s[0:1]
	s_cbranch_execz .Lsmp_skip_1
	v_add_f32_e32 v97, v97, v110
	v_lshlrev_b32_e32 v46, 16, v171
	v_fma_f32 v48, v96, v46, v97
	v_mul_f32_e32 v46, 0x3d372713, v48
	v_mul_f32_e32 v46, v48, v46
	v_fma_f32 v46, v48, v46, v48
	v_mul_f32_e32 v46, 0xbfcc422a, v46
	v_mul_f32_e32 v46, 0x3fb8aa3b, v46
	v_exp_f32_e32 v46, v46
	v_lshl_add_u64 v[98:99], v[44:45], 0, s[44:45]
	v_add_f32_e32 v46, 1.0, v46
	v_rcp_f32_e32 v46, v46
	s_nop 0
	v_mul_f32_e32 v46, v48, v46
	v_cvt_pk_bf16_f32 v46, v46, v46
	global_store_short v[98:99], v46, off
.Lsmp_skip_1:
	s_or_b64 exec, exec, s[60:61]
	s_add_u32 s44, s44, 0x400
	s_addc_u32 s45, s45, 0
	v_lshlrev_b32_e32 v46, 16, v138
	v_and_b32_e32 v48, 0xffff0000, v138
	v_lshlrev_b32_e32 v50, 16, v139
	v_and_b32_e32 v52, 0xffff0000, v139
	v_pk_fma_f32 v[98:99], v[2:3], v[46:47], 0 op_sel_hi:[1,0,0]
	v_lshlrev_b32_e32 v54, 16, v140
	v_pk_fma_f32 v[98:99], v[42:43], v[48:49], v[98:99] op_sel_hi:[1,0,1]
	v_and_b32_e32 v56, 0xffff0000, v140
	v_pk_fma_f32 v[98:99], v[4:5], v[50:51], v[98:99] op_sel_hi:[1,0,1]
	v_lshlrev_b32_e32 v58, 16, v141
	v_pk_fma_f32 v[98:99], v[40:41], v[52:53], v[98:99] op_sel_hi:[1,0,1]
	v_and_b32_e32 v60, 0xffff0000, v141
	v_pk_fma_f32 v[98:99], v[6:7], v[54:55], v[98:99] op_sel_hi:[1,0,1]
	v_lshlrev_b32_e32 v62, 16, v142
	v_pk_fma_f32 v[98:99], v[38:39], v[56:57], v[98:99] op_sel_hi:[1,0,1]
	v_and_b32_e32 v64, 0xffff0000, v142
	v_pk_fma_f32 v[98:99], v[8:9], v[58:59], v[98:99] op_sel_hi:[1,0,1]
	v_lshlrev_b32_e32 v66, 16, v143
	v_pk_fma_f32 v[98:99], v[36:37], v[60:61], v[98:99] op_sel_hi:[1,0,1]
	v_and_b32_e32 v68, 0xffff0000, v143
	v_pk_fma_f32 v[98:99], v[10:11], v[62:63], v[98:99] op_sel_hi:[1,0,1]
	v_lshlrev_b32_e32 v70, 16, v144
	v_pk_fma_f32 v[98:99], v[34:35], v[64:65], v[98:99] op_sel_hi:[1,0,1]
	v_and_b32_e32 v72, 0xffff0000, v144
	v_pk_fma_f32 v[98:99], v[12:13], v[66:67], v[98:99] op_sel_hi:[1,0,1]
	v_lshlrev_b32_e32 v74, 16, v145
	v_pk_fma_f32 v[98:99], v[32:33], v[68:69], v[98:99] op_sel_hi:[1,0,1]
	v_and_b32_e32 v76, 0xffff0000, v145
	v_pk_fma_f32 v[98:99], v[14:15], v[70:71], v[98:99] op_sel_hi:[1,0,1]
	s_nop 0
	v_pk_fma_f32 v[98:99], v[30:31], v[72:73], v[98:99] op_sel_hi:[1,0,1]
	s_nop 0
	v_pk_fma_f32 v[98:99], v[16:17], v[74:75], v[98:99] op_sel_hi:[1,0,1]
	s_nop 0
	v_pk_fma_f32 v[98:99], v[28:29], v[76:77], v[98:99] op_sel_hi:[1,0,1]
	s_nop 0
	v_pk_fma_f32 v[98:99], v[26:27], v[22:23], v[98:99] op_sel:[0,1,0] op_sel_hi:[1,0,1]
	s_nop 0
	v_pk_fma_f32 v[22:23], v[24:25], v[22:23], v[98:99]
	s_nop 0
	v_mul_f32_e32 v97, v67, v22
	v_mul_f32_e32 v98, v69, v22
	v_mul_f32_e32 v99, v71, v22
	v_mul_f32_e32 v100, v73, v22
	v_mul_f32_e32 v101, v75, v22
	v_mul_f32_e32 v102, v77, v22
	v_mul_f32_e32 v109, v78, v22
	v_mul_f32_e32 v111, v79, v22
	v_mul_f32_e32 v113, v88, v22
	v_mul_f32_e32 v115, v89, v22
	v_mul_f32_e32 v117, v90, v22
	v_mul_f32_e32 v119, v91, v22
	v_mul_f32_e32 v121, v92, v22
	v_mul_f32_e32 v123, v93, v22
	v_mul_f32_e32 v125, v94, v22
	v_mul_f32_e32 v127, v95, v22
	v_fma_f32 v97, v51, v23, -v97
	v_fma_f32 v98, v53, v23, -v98
	v_fma_f32 v99, v55, v23, -v99
	v_fma_f32 v100, v57, v23, -v100
	v_fma_f32 v101, v59, v23, -v101
	v_fma_f32 v102, v61, v23, -v102
	v_fma_f32 v109, v63, v23, -v109
	v_fma_f32 v111, v65, v23, -v111
	v_fma_f32 v113, v80, v23, -v113
	v_fma_f32 v115, v81, v23, -v115
	v_fma_f32 v117, v82, v23, -v117
	v_fma_f32 v119, v83, v23, -v119
	v_fma_f32 v121, v84, v23, -v121
	v_fma_f32 v123, v85, v23, -v123
	v_fma_f32 v125, v86, v23, -v125
	v_fma_f32 v127, v87, v23, -v127
	v_add_f32_dpp v97, v97, v97 row_ror:8 row_mask:0xf bank_mask:0xf bound_ctrl:1
	v_add_f32_dpp v98, v98, v98 row_ror:8 row_mask:0xf bank_mask:0xf bound_ctrl:1
	v_add_f32_dpp v99, v99, v99 row_ror:8 row_mask:0xf bank_mask:0xf bound_ctrl:1
	v_add_f32_dpp v100, v100, v100 row_ror:8 row_mask:0xf bank_mask:0xf bound_ctrl:1
	v_add_f32_dpp v101, v101, v101 row_ror:8 row_mask:0xf bank_mask:0xf bound_ctrl:1
	v_add_f32_dpp v102, v102, v102 row_ror:8 row_mask:0xf bank_mask:0xf bound_ctrl:1
	v_add_f32_dpp v109, v109, v109 row_ror:8 row_mask:0xf bank_mask:0xf bound_ctrl:1
	v_add_f32_dpp v111, v111, v111 row_ror:8 row_mask:0xf bank_mask:0xf bound_ctrl:1
	v_add_f32_dpp v113, v113, v113 row_ror:8 row_mask:0xf bank_mask:0xf bound_ctrl:1
	v_add_f32_dpp v115, v115, v115 row_ror:8 row_mask:0xf bank_mask:0xf bound_ctrl:1
	v_add_f32_dpp v117, v117, v117 row_ror:8 row_mask:0xf bank_mask:0xf bound_ctrl:1
	v_add_f32_dpp v119, v119, v119 row_ror:8 row_mask:0xf bank_mask:0xf bound_ctrl:1
	v_add_f32_dpp v121, v121, v121 row_ror:8 row_mask:0xf bank_mask:0xf bound_ctrl:1
	v_add_f32_dpp v123, v123, v123 row_ror:8 row_mask:0xf bank_mask:0xf bound_ctrl:1
	v_add_f32_dpp v125, v125, v125 row_ror:8 row_mask:0xf bank_mask:0xf bound_ctrl:1
	v_add_f32_dpp v127, v127, v127 row_ror:8 row_mask:0xf bank_mask:0xf bound_ctrl:1
	v_cndmask_b32_e64 v97, v97, v113, s[6:7]
	v_cndmask_b32_e64 v98, v98, v115, s[6:7]
	v_cndmask_b32_e64 v99, v99, v117, s[6:7]
	v_cndmask_b32_e64 v100, v100, v119, s[6:7]
	v_cndmask_b32_e64 v101, v101, v121, s[6:7]
	v_cndmask_b32_e64 v102, v102, v123, s[6:7]
	v_cndmask_b32_e64 v109, v109, v125, s[6:7]
	v_cndmask_b32_e64 v111, v111, v127, s[6:7]
	v_add_f32_dpp v97, v97, v97 row_half_mirror row_mask:0xf bank_mask:0xf bound_ctrl:1
	v_add_f32_dpp v98, v98, v98 row_half_mirror row_mask:0xf bank_mask:0xf bound_ctrl:1
	v_add_f32_dpp v99, v99, v99 row_half_mirror row_mask:0xf bank_mask:0xf bound_ctrl:1
	v_add_f32_dpp v100, v100, v100 row_half_mirror row_mask:0xf bank_mask:0xf bound_ctrl:1
	v_add_f32_dpp v101, v101, v101 row_half_mirror row_mask:0xf bank_mask:0xf bound_ctrl:1
	v_add_f32_dpp v102, v102, v102 row_half_mirror row_mask:0xf bank_mask:0xf bound_ctrl:1
	v_add_f32_dpp v109, v109, v109 row_half_mirror row_mask:0xf bank_mask:0xf bound_ctrl:1
	v_add_f32_dpp v111, v111, v111 row_half_mirror row_mask:0xf bank_mask:0xf bound_ctrl:1
	v_cndmask_b32_e64 v97, v97, v101, s[8:9]
	v_cndmask_b32_e64 v98, v98, v102, s[8:9]
	v_cndmask_b32_e64 v99, v99, v109, s[8:9]
	v_cndmask_b32_e64 v100, v100, v111, s[8:9]
	v_add_f32_dpp v97, v97, v97 quad_perm:[3,2,1,0] row_mask:0xf bank_mask:0xf bound_ctrl:1
	v_add_f32_dpp v98, v98, v98 quad_perm:[3,2,1,0] row_mask:0xf bank_mask:0xf bound_ctrl:1
	v_add_f32_dpp v99, v99, v99 quad_perm:[3,2,1,0] row_mask:0xf bank_mask:0xf bound_ctrl:1
	v_add_f32_dpp v100, v100, v100 quad_perm:[3,2,1,0] row_mask:0xf bank_mask:0xf bound_ctrl:1
	v_cndmask_b32_e64 v97, v97, v99, s[10:11]
	v_cndmask_b32_e64 v98, v98, v100, s[10:11]
	s_nop 1
	v_add_f32_dpp v97, v97, v97 quad_perm:[1,0,3,2] row_mask:0xf bank_mask:0xf bound_ctrl:1
	v_add_f32_dpp v98, v98, v98 quad_perm:[1,0,3,2] row_mask:0xf bank_mask:0xf bound_ctrl:1
	v_cndmask_b32_e64 v97, v97, v98, s[12:13]
	v_mov_b32_e32 v110, v97
	s_nop 1
	v_permlane16_swap_b32_e32 v97, v110
	v_add_f32_e32 v97, v97, v110
	v_mov_b32_e32 v110, v97
	s_nop 1
	v_permlane32_swap_b32_e32 v97, v110
	s_and_saveexec_b64 s[60:61], s[0:1]
	s_cbranch_execz .Lsmp_skip_2
	v_add_f32_e32 v97, v97, v110
	v_lshlrev_b32_e32 v46, 16, v172
	v_fma_f32 v48, v96, v46, v97
	v_mul_f32_e32 v46, 0x3d372713, v48
	v_mul_f32_e32 v46, v48, v46
	v_fma_f32 v46, v48, v46, v48
	v_mul_f32_e32 v46, 0xbfcc422a, v46
	v_mul_f32_e32 v46, 0x3fb8aa3b, v46
	v_exp_f32_e32 v46, v46
	v_lshl_add_u64 v[98:99], v[44:45], 0, s[44:45]
	v_add_f32_e32 v46, 1.0, v46
	v_rcp_f32_e32 v46, v46
	s_nop 0
	v_mul_f32_e32 v46, v48, v46
	v_cvt_pk_bf16_f32 v46, v46, v46
	global_store_short v[98:99], v46, off
.Lsmp_skip_2:
	s_or_b64 exec, exec, s[60:61]
	s_add_u32 s44, s44, 0x400
	s_addc_u32 s45, s45, 0
	v_lshlrev_b32_e32 v46, 16, v150
	v_and_b32_e32 v48, 0xffff0000, v150
	v_lshlrev_b32_e32 v50, 16, v151
	v_and_b32_e32 v52, 0xffff0000, v151
	v_pk_fma_f32 v[98:99], v[2:3], v[46:47], 0 op_sel_hi:[1,0,0]
	v_lshlrev_b32_e32 v54, 16, v152
	v_pk_fma_f32 v[98:99], v[42:43], v[48:49], v[98:99] op_sel_hi:[1,0,1]
	v_and_b32_e32 v56, 0xffff0000, v152
	v_pk_fma_f32 v[98:99], v[4:5], v[50:51], v[98:99] op_sel_hi:[1,0,1]
	v_lshlrev_b32_e32 v58, 16, v153
	v_pk_fma_f32 v[98:99], v[40:41], v[52:53], v[98:99] op_sel_hi:[1,0,1]
	v_and_b32_e32 v60, 0xffff0000, v153
	v_pk_fma_f32 v[98:99], v[6:7], v[54:55], v[98:99] op_sel_hi:[1,0,1]
	v_lshlrev_b32_e32 v62, 16, v154
	v_pk_fma_f32 v[98:99], v[38:39], v[56:57], v[98:99] op_sel_hi:[1,0,1]
	v_and_b32_e32 v64, 0xffff0000, v154
	v_pk_fma_f32 v[98:99], v[8:9], v[58:59], v[98:99] op_sel_hi:[1,0,1]
	v_lshlrev_b32_e32 v66, 16, v155
	v_pk_fma_f32 v[98:99], v[36:37], v[60:61], v[98:99] op_sel_hi:[1,0,1]
	v_and_b32_e32 v68, 0xffff0000, v155
	v_pk_fma_f32 v[98:99], v[10:11], v[62:63], v[98:99] op_sel_hi:[1,0,1]
	v_lshlrev_b32_e32 v70, 16, v156
	v_pk_fma_f32 v[98:99], v[34:35], v[64:65], v[98:99] op_sel_hi:[1,0,1]
	v_and_b32_e32 v72, 0xffff0000, v156
	v_pk_fma_f32 v[98:99], v[12:13], v[66:67], v[98:99] op_sel_hi:[1,0,1]
	v_lshlrev_b32_e32 v74, 16, v157
	v_pk_fma_f32 v[98:99], v[32:33], v[68:69], v[98:99] op_sel_hi:[1,0,1]
	v_and_b32_e32 v76, 0xffff0000, v157
	v_pk_fma_f32 v[98:99], v[14:15], v[70:71], v[98:99] op_sel_hi:[1,0,1]
	s_nop 0
	v_pk_fma_f32 v[98:99], v[30:31], v[72:73], v[98:99] op_sel_hi:[1,0,1]
	s_nop 0
	v_pk_fma_f32 v[98:99], v[16:17], v[74:75], v[98:99] op_sel_hi:[1,0,1]
	s_nop 0
	v_pk_fma_f32 v[98:99], v[28:29], v[76:77], v[98:99] op_sel_hi:[1,0,1]
	s_nop 0
	v_pk_fma_f32 v[98:99], v[26:27], v[22:23], v[98:99] op_sel:[0,1,0] op_sel_hi:[1,0,1]
	s_nop 0
	v_pk_fma_f32 v[22:23], v[24:25], v[22:23], v[98:99]
	s_nop 0
	v_mul_f32_e32 v97, v67, v22
	v_mul_f32_e32 v98, v69, v22
	v_mul_f32_e32 v99, v71, v22
	v_mul_f32_e32 v100, v73, v22
	v_mul_f32_e32 v101, v75, v22
	v_mul_f32_e32 v102, v77, v22
	v_mul_f32_e32 v109, v78, v22
	v_mul_f32_e32 v111, v79, v22
	v_mul_f32_e32 v113, v88, v22
	v_mul_f32_e32 v115, v89, v22
	v_mul_f32_e32 v117, v90, v22
	v_mul_f32_e32 v119, v91, v22
	v_mul_f32_e32 v121, v92, v22
	v_mul_f32_e32 v123, v93, v22
	v_mul_f32_e32 v125, v94, v22
	v_mul_f32_e32 v127, v95, v22
	v_fma_f32 v97, v51, v23, -v97
	v_fma_f32 v98, v53, v23, -v98
	v_fma_f32 v99, v55, v23, -v99
	v_fma_f32 v100, v57, v23, -v100
	v_fma_f32 v101, v59, v23, -v101
	v_fma_f32 v102, v61, v23, -v102
	v_fma_f32 v109, v63, v23, -v109
	v_fma_f32 v111, v65, v23, -v111
	v_fma_f32 v113, v80, v23, -v113
	v_fma_f32 v115, v81, v23, -v115
	v_fma_f32 v117, v82, v23, -v117
	v_fma_f32 v119, v83, v23, -v119
	v_fma_f32 v121, v84, v23, -v121
	v_fma_f32 v123, v85, v23, -v123
	v_fma_f32 v125, v86, v23, -v125
	v_fma_f32 v127, v87, v23, -v127
	v_add_f32_dpp v97, v97, v97 row_ror:8 row_mask:0xf bank_mask:0xf bound_ctrl:1
	v_add_f32_dpp v98, v98, v98 row_ror:8 row_mask:0xf bank_mask:0xf bound_ctrl:1
	v_add_f32_dpp v99, v99, v99 row_ror:8 row_mask:0xf bank_mask:0xf bound_ctrl:1
	v_add_f32_dpp v100, v100, v100 row_ror:8 row_mask:0xf bank_mask:0xf bound_ctrl:1
	v_add_f32_dpp v101, v101, v101 row_ror:8 row_mask:0xf bank_mask:0xf bound_ctrl:1
	v_add_f32_dpp v102, v102, v102 row_ror:8 row_mask:0xf bank_mask:0xf bound_ctrl:1
	v_add_f32_dpp v109, v109, v109 row_ror:8 row_mask:0xf bank_mask:0xf bound_ctrl:1
	v_add_f32_dpp v111, v111, v111 row_ror:8 row_mask:0xf bank_mask:0xf bound_ctrl:1
	v_add_f32_dpp v113, v113, v113 row_ror:8 row_mask:0xf bank_mask:0xf bound_ctrl:1
	v_add_f32_dpp v115, v115, v115 row_ror:8 row_mask:0xf bank_mask:0xf bound_ctrl:1
	v_add_f32_dpp v117, v117, v117 row_ror:8 row_mask:0xf bank_mask:0xf bound_ctrl:1
	v_add_f32_dpp v119, v119, v119 row_ror:8 row_mask:0xf bank_mask:0xf bound_ctrl:1
	v_add_f32_dpp v121, v121, v121 row_ror:8 row_mask:0xf bank_mask:0xf bound_ctrl:1
	v_add_f32_dpp v123, v123, v123 row_ror:8 row_mask:0xf bank_mask:0xf bound_ctrl:1
	v_add_f32_dpp v125, v125, v125 row_ror:8 row_mask:0xf bank_mask:0xf bound_ctrl:1
	v_add_f32_dpp v127, v127, v127 row_ror:8 row_mask:0xf bank_mask:0xf bound_ctrl:1
	v_cndmask_b32_e64 v97, v97, v113, s[6:7]
	v_cndmask_b32_e64 v98, v98, v115, s[6:7]
	v_cndmask_b32_e64 v99, v99, v117, s[6:7]
	v_cndmask_b32_e64 v100, v100, v119, s[6:7]
	v_cndmask_b32_e64 v101, v101, v121, s[6:7]
	v_cndmask_b32_e64 v102, v102, v123, s[6:7]
	v_cndmask_b32_e64 v109, v109, v125, s[6:7]
	v_cndmask_b32_e64 v111, v111, v127, s[6:7]
	v_add_f32_dpp v97, v97, v97 row_half_mirror row_mask:0xf bank_mask:0xf bound_ctrl:1
	v_add_f32_dpp v98, v98, v98 row_half_mirror row_mask:0xf bank_mask:0xf bound_ctrl:1
	v_add_f32_dpp v99, v99, v99 row_half_mirror row_mask:0xf bank_mask:0xf bound_ctrl:1
	v_add_f32_dpp v100, v100, v100 row_half_mirror row_mask:0xf bank_mask:0xf bound_ctrl:1
	v_add_f32_dpp v101, v101, v101 row_half_mirror row_mask:0xf bank_mask:0xf bound_ctrl:1
	v_add_f32_dpp v102, v102, v102 row_half_mirror row_mask:0xf bank_mask:0xf bound_ctrl:1
	v_add_f32_dpp v109, v109, v109 row_half_mirror row_mask:0xf bank_mask:0xf bound_ctrl:1
	v_add_f32_dpp v111, v111, v111 row_half_mirror row_mask:0xf bank_mask:0xf bound_ctrl:1
	v_cndmask_b32_e64 v97, v97, v101, s[8:9]
	v_cndmask_b32_e64 v98, v98, v102, s[8:9]
	v_cndmask_b32_e64 v99, v99, v109, s[8:9]
	v_cndmask_b32_e64 v100, v100, v111, s[8:9]
	v_add_f32_dpp v97, v97, v97 quad_perm:[3,2,1,0] row_mask:0xf bank_mask:0xf bound_ctrl:1
	v_add_f32_dpp v98, v98, v98 quad_perm:[3,2,1,0] row_mask:0xf bank_mask:0xf bound_ctrl:1
	v_add_f32_dpp v99, v99, v99 quad_perm:[3,2,1,0] row_mask:0xf bank_mask:0xf bound_ctrl:1
	v_add_f32_dpp v100, v100, v100 quad_perm:[3,2,1,0] row_mask:0xf bank_mask:0xf bound_ctrl:1
	v_cndmask_b32_e64 v97, v97, v99, s[10:11]
	v_cndmask_b32_e64 v98, v98, v100, s[10:11]
	s_nop 1
	v_add_f32_dpp v97, v97, v97 quad_perm:[1,0,3,2] row_mask:0xf bank_mask:0xf bound_ctrl:1
	v_add_f32_dpp v98, v98, v98 quad_perm:[1,0,3,2] row_mask:0xf bank_mask:0xf bound_ctrl:1
	v_cndmask_b32_e64 v97, v97, v98, s[12:13]
	v_mov_b32_e32 v110, v97
	s_nop 1
	v_permlane16_swap_b32_e32 v97, v110
	v_add_f32_e32 v97, v97, v110
	v_mov_b32_e32 v110, v97
	s_nop 1
	v_permlane32_swap_b32_e32 v97, v110
	s_and_saveexec_b64 s[60:61], s[0:1]
	s_cbranch_execz .Lsmp_skip_3
	v_add_f32_e32 v97, v97, v110
	v_lshlrev_b32_e32 v46, 16, v173
	v_fma_f32 v48, v96, v46, v97
	v_mul_f32_e32 v46, 0x3d372713, v48
	v_mul_f32_e32 v46, v48, v46
	v_fma_f32 v46, v48, v46, v48
	v_mul_f32_e32 v46, 0xbfcc422a, v46
	v_mul_f32_e32 v46, 0x3fb8aa3b, v46
	v_exp_f32_e32 v46, v46
	v_lshl_add_u64 v[98:99], v[44:45], 0, s[44:45]
	v_add_f32_e32 v46, 1.0, v46
	v_rcp_f32_e32 v46, v46
	s_nop 0
	v_mul_f32_e32 v46, v48, v46
	v_cvt_pk_bf16_f32 v46, v46, v46
	global_store_short v[98:99], v46, off
.Lsmp_skip_3:
	s_or_b64 exec, exec, s[60:61]
.LBB0_1080:
	s_and_b64 vcc, exec, s[58:59]
	s_cbranch_vccz .LBB0_1082
	s_ashr_i32 s5, s4, 31
	s_lshl_b64 s[4:5], s[4:5], 2
	v_readlane_b32 s68, v252, 4
	v_readlane_b32 s69, v252, 5
	s_add_u32 s4, s68, s4
	s_addc_u32 s5, s69, s5
	v_lshl_add_u64 v[2:3], v[18:19], 2, s[4:5]
	v_add_co_u32_e32 v4, vcc, 0x8408000, v2
	v_readlane_b32 s70, v252, 6
	s_nop 0
	v_addc_co_u32_e32 v5, vcc, 0, v3, vcc
	v_add_co_u32_e32 v2, vcc, 0x8508000, v2
	v_readlane_b32 s71, v252, 7
	s_nop 0
	v_addc_co_u32_e32 v3, vcc, 0, v3, vcc
	global_store_dword v[4:5], v23, off
	global_store_dword v[2:3], v22, off
